# attnA steps A and B: softmax head of the current tile issued inside the next tile's QK MFMA shadows
# speedup vs baseline: 1.0091x; 1.0042x over previous
.LBB0_1381:
	ds_read_b128 v[2:5], v222
	ds_read_b128 v[6:9], v222 offset:4096
	ds_read_b128 v[10:13], v223
	ds_read_b128 v[244:247], v223 offset:4096
	s_waitcnt lgkmcnt(3)
	v_mfma_f32_32x32x16_bf16 v[32:47], v[2:5], v[160:163], v[16:31]
	v_exp_f32_e32 v128, v128
	v_exp_f32_e32 v129, v129
	ds_read_b128 v[2:5], v224
	s_waitcnt lgkmcnt(3)
	v_mfma_f32_32x32x16_bf16 v[48:63], v[6:9], v[160:163], v[16:31]
	v_exp_f32_e32 v130, v130
	v_exp_f32_e32 v131, v131
	ds_read_b128 v[6:9], v224 offset:4096
	s_waitcnt lgkmcnt(3)
	v_mfma_f32_32x32x16_bf16 v[32:47], v[10:13], v[164:167], v[32:47]
	v_exp_f32_e32 v132, v132
	v_exp_f32_e32 v133, v133
	v_add_f32_e32 v0, 0, v128
	ds_read_b128 v[10:13], v225
	s_waitcnt lgkmcnt(3)
	v_mfma_f32_32x32x16_bf16 v[48:63], v[244:247], v[164:167], v[48:63]
	v_exp_f32_e32 v134, v134
	v_exp_f32_e32 v135, v135
	v_add_f32_e32 v0, v129, v0
	ds_read_b128 v[244:247], v225 offset:4096
	s_waitcnt lgkmcnt(3)
	v_mfma_f32_32x32x16_bf16 v[32:47], v[2:5], v[168:171], v[32:47]
	v_cvt_pk_bf16_f32 v208, v128, v129
	v_add_f32_e32 v0, v130, v0
	v_add_f32_e32 v0, v131, v0
	s_waitcnt lgkmcnt(2)
	v_mfma_f32_32x32x16_bf16 v[48:63], v[6:9], v[168:171], v[48:63]
	v_cvt_pk_bf16_f32 v209, v130, v131
	v_add_f32_e32 v0, v132, v0
	v_add_f32_e32 v0, v133, v0
	s_waitcnt lgkmcnt(1)
	v_mfma_f32_32x32x16_bf16 v[32:47], v[10:13], v[172:175], v[32:47]
	v_cvt_pk_bf16_f32 v210, v132, v133
	v_add_f32_e32 v0, v134, v0
	s_waitcnt lgkmcnt(0)
	v_mfma_f32_32x32x16_bf16 v[48:63], v[244:247], v[172:175], v[48:63]
	v_cvt_pk_bf16_f32 v211, v134, v135
	v_add_f32_e32 v0, v135, v0
	s_or_b64 exec, exec, s[20:21]
	s_and_saveexec_b64 s[20:21], s[4:5]
	ds_read_b64 v[6:7], v228 offset:32768
	ds_read_b64 v[8:9], v229 offset:32768
	ds_read_b64 v[10:11], v230 offset:45056
	ds_read_b64 v[12:13], v231 offset:45056
	ds_read_b64 v[244:245], v230 offset:36864
	ds_read_b64 v[246:247], v231 offset:36864
	ds_read_b64 v[128:129], v230 offset:40960
	ds_read_b64 v[130:131], v231 offset:40960
	ds_read_b64 v[132:133], v232 offset:32768
	ds_read_b64 v[134:135], v233 offset:32768
	s_waitcnt lgkmcnt(8)
	v_mfma_f32_32x32x16_bf16 v[112:127], v[6:9], v[208:211], v[112:127]
	ds_read_b64 v[6:7], v234 offset:45056
	ds_read_b64 v[8:9], v235 offset:45056
	v_exp_f32_e32 v136, v136
	v_exp_f32_e32 v137, v137
	s_waitcnt lgkmcnt(8)
	v_mfma_f32_32x32x16_bf16 v[64:79], v[10:13], v[208:211], v[64:79]
	ds_read_b64 v[10:11], v234 offset:36864
	ds_read_b64 v[12:13], v235 offset:36864
	v_exp_f32_e32 v138, v138
	v_exp_f32_e32 v139, v139
	v_add_f32_e32 v0, v136, v0
	v_add_f32_e32 v0, v137, v0
	s_waitcnt lgkmcnt(8)
	v_mfma_f32_32x32x16_bf16 v[96:111], v[244:247], v[208:211], v[96:111]
	ds_read_b64 v[244:245], v234 offset:40960
	ds_read_b64 v[246:247], v235 offset:40960
	v_exp_f32_e32 v140, v140
	v_exp_f32_e32 v141, v141
	v_add_f32_e32 v0, v138, v0
	v_add_f32_e32 v0, v139, v0
	s_waitcnt lgkmcnt(8)
	v_mfma_f32_32x32x16_bf16 v[80:95], v[128:131], v[208:211], v[80:95]
	ds_read_b64 v[128:129], v236 offset:32768
	ds_read_b64 v[130:131], v237 offset:32768
	v_exp_f32_e32 v142, v142
	v_exp_f32_e32 v143, v143
	v_add_f32_e32 v0, v140, v0
	v_add_f32_e32 v0, v141, v0
	v_add_f32_e32 v0, v142, v0
	v_add_f32_e32 v0, v143, v0
	v_cvt_pk_bf16_f32 v2, v136, v137
	v_cvt_pk_bf16_f32 v3, v138, v139
	v_cvt_pk_bf16_f32 v4, v140, v141
	v_cvt_pk_bf16_f32 v5, v142, v143
	s_nop 1
	ds_read_b64 v[136:137], v238 offset:45056
	ds_read_b64 v[138:139], v239 offset:45056
	s_waitcnt lgkmcnt(10)
	v_mfma_f32_32x32x16_bf16 v[112:127], v[132:135], v[2:5], v[112:127]
	ds_read_b64 v[140:141], v238 offset:36864
	ds_read_b64 v[142:143], v239 offset:36864
	v_exp_f32_e32 v144, v144
	v_exp_f32_e32 v145, v145
	s_waitcnt lgkmcnt(10)
	v_mfma_f32_32x32x16_bf16 v[64:79], v[6:9], v[2:5], v[64:79]
	ds_read_b64 v[132:133], v238 offset:40960
	ds_read_b64 v[134:135], v239 offset:40960
	v_exp_f32_e32 v146, v146
	v_exp_f32_e32 v147, v147
	v_add_f32_e32 v0, v144, v0
	v_add_f32_e32 v0, v145, v0
	s_waitcnt lgkmcnt(10)
	v_mfma_f32_32x32x16_bf16 v[96:111], v[10:13], v[2:5], v[96:111]
	ds_read_b64 v[6:7], v240 offset:32768
	ds_read_b64 v[8:9], v241 offset:32768
	v_exp_f32_e32 v148, v148
	v_exp_f32_e32 v149, v149
	v_add_f32_e32 v0, v146, v0
	v_add_f32_e32 v0, v147, v0
	s_waitcnt lgkmcnt(10)
	v_mfma_f32_32x32x16_bf16 v[80:95], v[244:247], v[2:5], v[80:95]
	ds_read_b64 v[10:11], v242 offset:36864
	ds_read_b64 v[12:13], v243 offset:36864
	v_exp_f32_e32 v150, v150
	v_exp_f32_e32 v151, v151
	v_add_f32_e32 v0, v148, v0
	v_add_f32_e32 v0, v149, v0
	v_add_f32_e32 v0, v150, v0
	v_add_f32_e32 v0, v151, v0
	v_cvt_pk_bf16_f32 v2, v144, v145
	v_cvt_pk_bf16_f32 v3, v146, v147
	v_cvt_pk_bf16_f32 v4, v148, v149
	v_cvt_pk_bf16_f32 v5, v150, v151
	s_nop 1
	ds_read_b64 v[244:245], v242 offset:40960
	ds_read_b64 v[246:247], v243 offset:40960
	s_waitcnt lgkmcnt(12)
	v_mfma_f32_32x32x16_bf16 v[112:127], v[128:131], v[2:5], v[112:127]
	ds_read_b64 v[144:145], v242 offset:45056
	ds_read_b64 v[146:147], v243 offset:45056
	v_exp_f32_e32 v152, v152
	v_exp_f32_e32 v153, v153
	s_waitcnt lgkmcnt(12)
	v_mfma_f32_32x32x16_bf16 v[64:79], v[136:139], v[2:5], v[64:79]
	v_exp_f32_e32 v154, v154
	v_exp_f32_e32 v155, v155
	v_add_f32_e32 v0, v152, v0
	v_add_f32_e32 v0, v153, v0
	s_waitcnt lgkmcnt(10)
	v_mfma_f32_32x32x16_bf16 v[96:111], v[140:143], v[2:5], v[96:111]
	v_exp_f32_e32 v156, v156
	v_exp_f32_e32 v157, v157
	v_add_f32_e32 v0, v154, v0
	v_add_f32_e32 v0, v155, v0
	s_waitcnt lgkmcnt(8)
	v_mfma_f32_32x32x16_bf16 v[80:95], v[132:135], v[2:5], v[80:95]
	v_exp_f32_e32 v158, v158
	v_exp_f32_e32 v159, v159
	v_add_f32_e32 v0, v156, v0
	v_add_f32_e32 v0, v157, v0
	v_add_f32_e32 v0, v158, v0
	v_add_f32_e32 v0, v159, v0
	v_cvt_pk_bf16_f32 v2, v152, v153
	v_cvt_pk_bf16_f32 v3, v154, v155
	v_cvt_pk_bf16_f32 v4, v156, v157
	v_cvt_pk_bf16_f32 v5, v158, v159
	s_nop 1
	s_waitcnt lgkmcnt(6)
	v_mfma_f32_32x32x16_bf16 v[112:127], v[6:9], v[2:5], v[112:127]
	s_waitcnt lgkmcnt(4)
	v_mfma_f32_32x32x16_bf16 v[96:111], v[10:13], v[2:5], v[96:111]
	s_waitcnt lgkmcnt(2)
	v_mfma_f32_32x32x16_bf16 v[80:95], v[244:247], v[2:5], v[80:95]
	s_waitcnt lgkmcnt(0)
	v_mfma_f32_32x32x16_bf16 v[64:79], v[144:147], v[2:5], v[64:79]
	v_add_f32_e32 v227, v0, v227
	s_branch .LBB0_1386

.LBB0_1423:
	ds_read_b128 v[2:5], v220
	ds_read_b128 v[6:9], v220 offset:4096
	ds_read_b128 v[10:13], v221
	ds_read_b128 v[244:247], v221 offset:4096
	s_waitcnt lgkmcnt(3)
	v_mfma_f32_32x32x16_bf16 v[80:95], v[2:5], v[160:163], v[16:31]
	v_exp_f32_e32 v128, v128
	v_exp_f32_e32 v129, v129
	ds_read_b128 v[2:5], v222
	s_waitcnt lgkmcnt(3)
	v_mfma_f32_32x32x16_bf16 v[96:111], v[6:9], v[160:163], v[16:31]
	v_exp_f32_e32 v130, v130
	v_exp_f32_e32 v131, v131
	ds_read_b128 v[6:9], v222 offset:4096
	s_waitcnt lgkmcnt(3)
	v_mfma_f32_32x32x16_bf16 v[80:95], v[10:13], v[164:167], v[80:95]
	v_exp_f32_e32 v132, v132
	v_exp_f32_e32 v133, v133
	v_add_f32_e32 v0, 0, v128
	ds_read_b128 v[10:13], v223
	s_waitcnt lgkmcnt(3)
	v_mfma_f32_32x32x16_bf16 v[96:111], v[244:247], v[164:167], v[96:111]
	v_exp_f32_e32 v134, v134
	v_exp_f32_e32 v135, v135
	v_add_f32_e32 v0, v129, v0
	ds_read_b128 v[244:247], v223 offset:4096
	s_waitcnt lgkmcnt(3)
	v_mfma_f32_32x32x16_bf16 v[80:95], v[2:5], v[168:171], v[80:95]
	v_cvt_pk_bf16_f32 v208, v128, v129
	v_add_f32_e32 v0, v130, v0
	v_add_f32_e32 v0, v131, v0
	s_waitcnt lgkmcnt(2)
	v_mfma_f32_32x32x16_bf16 v[96:111], v[6:9], v[168:171], v[96:111]
	v_cvt_pk_bf16_f32 v209, v130, v131
	v_add_f32_e32 v0, v132, v0
	v_add_f32_e32 v0, v133, v0
	s_waitcnt lgkmcnt(1)
	v_mfma_f32_32x32x16_bf16 v[80:95], v[10:13], v[172:175], v[80:95]
	v_cvt_pk_bf16_f32 v210, v132, v133
	v_add_f32_e32 v0, v134, v0
	s_waitcnt lgkmcnt(0)
	v_mfma_f32_32x32x16_bf16 v[96:111], v[244:247], v[172:175], v[96:111]
	v_cvt_pk_bf16_f32 v211, v134, v135
	v_add_f32_e32 v0, v135, v0
	s_or_b64 exec, exec, s[20:21]
	s_and_saveexec_b64 s[20:21], s[4:5]
	ds_read_b64 v[6:7], v226 offset:32768
	ds_read_b64 v[8:9], v227 offset:32768
	ds_read_b64 v[10:11], v228 offset:45056
	ds_read_b64 v[12:13], v229 offset:45056
	ds_read_b64 v[242:243], v228 offset:36864
	ds_read_b64 v[244:245], v229 offset:36864
	ds_read_b64 v[128:129], v228 offset:40960
	ds_read_b64 v[130:131], v229 offset:40960
	ds_read_b64 v[132:133], v230 offset:32768
	ds_read_b64 v[134:135], v231 offset:32768
	s_waitcnt lgkmcnt(8)
	v_mfma_f32_32x32x16_bf16 v[64:79], v[6:9], v[208:211], v[64:79]
	ds_read_b64 v[6:7], v232 offset:45056
	ds_read_b64 v[8:9], v233 offset:45056
	v_exp_f32_e32 v136, v136
	v_exp_f32_e32 v137, v137
	s_waitcnt lgkmcnt(8)
	v_mfma_f32_32x32x16_bf16 v[112:127], v[10:13], v[208:211], v[112:127]
	ds_read_b64 v[10:11], v232 offset:36864
	ds_read_b64 v[12:13], v233 offset:36864
	v_exp_f32_e32 v138, v138
	v_exp_f32_e32 v139, v139
	v_add_f32_e32 v0, v136, v0
	v_add_f32_e32 v0, v137, v0
	s_waitcnt lgkmcnt(8)
	v_mfma_f32_32x32x16_bf16 v[48:63], v[242:245], v[208:211], v[48:63]
	ds_read_b64 v[242:243], v232 offset:40960
	ds_read_b64 v[244:245], v233 offset:40960
	v_exp_f32_e32 v140, v140
	v_exp_f32_e32 v141, v141
	v_add_f32_e32 v0, v138, v0
	v_add_f32_e32 v0, v139, v0
	s_waitcnt lgkmcnt(8)
	v_mfma_f32_32x32x16_bf16 v[32:47], v[128:131], v[208:211], v[32:47]
	ds_read_b64 v[128:129], v234 offset:32768
	ds_read_b64 v[130:131], v235 offset:32768
	v_exp_f32_e32 v142, v142
	v_exp_f32_e32 v143, v143
	v_add_f32_e32 v0, v140, v0
	v_add_f32_e32 v0, v141, v0
	v_add_f32_e32 v0, v142, v0
	v_add_f32_e32 v0, v143, v0
	v_cvt_pk_bf16_f32 v2, v136, v137
	v_cvt_pk_bf16_f32 v3, v138, v139
	v_cvt_pk_bf16_f32 v4, v140, v141
	v_cvt_pk_bf16_f32 v5, v142, v143
	s_nop 1
	ds_read_b64 v[136:137], v236 offset:45056
	ds_read_b64 v[138:139], v237 offset:45056
	s_waitcnt lgkmcnt(10)
	v_mfma_f32_32x32x16_bf16 v[64:79], v[132:135], v[2:5], v[64:79]
	ds_read_b64 v[140:141], v236 offset:36864
	ds_read_b64 v[142:143], v237 offset:36864
	v_exp_f32_e32 v144, v144
	v_exp_f32_e32 v145, v145
	s_waitcnt lgkmcnt(10)
	v_mfma_f32_32x32x16_bf16 v[112:127], v[6:9], v[2:5], v[112:127]
	ds_read_b64 v[132:133], v236 offset:40960
	ds_read_b64 v[134:135], v237 offset:40960
	v_exp_f32_e32 v146, v146
	v_exp_f32_e32 v147, v147
	v_add_f32_e32 v0, v144, v0
	v_add_f32_e32 v0, v145, v0
	s_waitcnt lgkmcnt(10)
	v_mfma_f32_32x32x16_bf16 v[48:63], v[10:13], v[2:5], v[48:63]
	ds_read_b64 v[6:7], v238 offset:32768
	ds_read_b64 v[8:9], v239 offset:32768
	v_exp_f32_e32 v148, v148
	v_exp_f32_e32 v149, v149
	v_add_f32_e32 v0, v146, v0
	v_add_f32_e32 v0, v147, v0
	s_waitcnt lgkmcnt(10)
	v_mfma_f32_32x32x16_bf16 v[32:47], v[242:245], v[2:5], v[32:47]
	ds_read_b64 v[10:11], v240 offset:36864
	ds_read_b64 v[12:13], v241 offset:36864
	v_exp_f32_e32 v150, v150
	v_exp_f32_e32 v151, v151
	v_add_f32_e32 v0, v148, v0
	v_add_f32_e32 v0, v149, v0
	v_add_f32_e32 v0, v150, v0
	v_add_f32_e32 v0, v151, v0
	v_cvt_pk_bf16_f32 v2, v144, v145
	v_cvt_pk_bf16_f32 v3, v146, v147
	v_cvt_pk_bf16_f32 v4, v148, v149
	v_cvt_pk_bf16_f32 v5, v150, v151
	s_nop 1
	ds_read_b64 v[242:243], v240 offset:40960
	ds_read_b64 v[244:245], v241 offset:40960
	s_waitcnt lgkmcnt(12)
	v_mfma_f32_32x32x16_bf16 v[64:79], v[128:131], v[2:5], v[64:79]
	ds_read_b64 v[144:145], v240 offset:45056
	ds_read_b64 v[146:147], v241 offset:45056
	v_exp_f32_e32 v152, v152
	v_exp_f32_e32 v153, v153
	s_waitcnt lgkmcnt(12)
	v_mfma_f32_32x32x16_bf16 v[112:127], v[136:139], v[2:5], v[112:127]
	v_exp_f32_e32 v154, v154
	v_exp_f32_e32 v155, v155
	v_add_f32_e32 v0, v152, v0
	v_add_f32_e32 v0, v153, v0
	s_waitcnt lgkmcnt(10)
	v_mfma_f32_32x32x16_bf16 v[48:63], v[140:143], v[2:5], v[48:63]
	v_exp_f32_e32 v156, v156
	v_exp_f32_e32 v157, v157
	v_add_f32_e32 v0, v154, v0
	v_add_f32_e32 v0, v155, v0
	s_waitcnt lgkmcnt(8)
	v_mfma_f32_32x32x16_bf16 v[32:47], v[132:135], v[2:5], v[32:47]
	v_exp_f32_e32 v158, v158
	v_exp_f32_e32 v159, v159
	v_add_f32_e32 v0, v156, v0
	v_add_f32_e32 v0, v157, v0
	v_add_f32_e32 v0, v158, v0
	v_add_f32_e32 v0, v159, v0
	v_cvt_pk_bf16_f32 v2, v152, v153
	v_cvt_pk_bf16_f32 v3, v154, v155
	v_cvt_pk_bf16_f32 v4, v156, v157
	v_cvt_pk_bf16_f32 v5, v158, v159
	s_nop 1
	s_waitcnt lgkmcnt(6)
	v_mfma_f32_32x32x16_bf16 v[64:79], v[6:9], v[2:5], v[64:79]
	s_waitcnt lgkmcnt(4)
	v_mfma_f32_32x32x16_bf16 v[48:63], v[10:13], v[2:5], v[48:63]
	s_waitcnt lgkmcnt(2)
	v_mfma_f32_32x32x16_bf16 v[32:47], v[242:245], v[2:5], v[32:47]
	s_waitcnt lgkmcnt(0)
	v_mfma_f32_32x32x16_bf16 v[112:127], v[144:147], v[2:5], v[112:127]
	v_add_f32_e32 v224, v0, v224
	s_branch .LBB0_1428
